# v34: ssd_out dt values prefetched one iteration ahead; mid-iteration dt waits removed so S3 prefetch drains late
# speedup vs baseline: 1.0075x; 1.0075x over previous
.LBB0_1334:
	s_or_b64 exec, exec, s[0:1]
	v_or_b32_e32 v70, s34, v157
	s_lshr_b32 s1, s74, 1
	v_or_b32_e32 v66, s72, v70
	s_lshr_b32 s0, s74, 2
	v_writelane_b32 v255, s34, 49
	v_ashrrev_i32_e32 v67, 31, v66
	s_and_b32 s42, s1, 1
	v_lshlrev_b64 v[66:67], 6, v[66:67]
	s_and_b32 s0, s0, 31
	s_lshl_b32 s43, s42, 3
	v_readlane_b32 s1, v255, 31
	v_readlane_b32 s56, v254, 46
	v_lshl_add_u64 v[66:67], s[28:29], 0, v[66:67]
	s_lshl_b32 s52, s18, 2
	s_lshl_b32 s40, s0, 7
	s_lshl_b32 s41, s0, 4
	s_add_i32 s0, s1, s43
	v_readlane_b32 s64, v254, 54
	v_readlane_b32 s65, v254, 55
	v_lshl_add_u64 v[66:67], v[66:67], 0, s[52:53]
	s_lshl_b32 s52, s42, 10
	s_lshl_b32 s0, s0, 2
	s_mov_b64 s[20:21], s[64:65]
	s_add_u32 s54, s20, s0
	v_or_b32_e32 v72, 1, v70
	v_cmp_gt_u32_e32 vcc, v160, v70
	s_addc_u32 s55, s21, 0
	v_or_b32_e32 v73, 2, v70
	s_or_b64 s[82:83], s[2:3], vcc
	v_cmp_gt_u32_e32 vcc, v160, v72
	v_or_b32_e32 v74, 3, v70
	s_or_b64 s[86:87], s[2:3], vcc
	v_cmp_gt_u32_e32 vcc, v160, v73
	s_or_b64 s[88:89], s[2:3], vcc
	v_cmp_gt_u32_e32 vcc, v160, v74
	s_or_b64 s[90:91], s[2:3], vcc
	v_cmp_gt_u32_e64 s[2:3], v161, v70
	v_readlane_b32 s57, v254, 47
	v_readlane_b32 s58, v254, 48
	v_readlane_b32 s59, v254, 49
	v_readlane_b32 s60, v254, 50
	v_readlane_b32 s61, v254, 51
	v_readlane_b32 s62, v254, 52
	v_readlane_b32 s63, v254, 53
	v_readlane_b32 s66, v254, 56
	v_readlane_b32 s67, v254, 57
	v_readlane_b32 s68, v254, 58
	v_readlane_b32 s69, v254, 59
	v_readlane_b32 s70, v254, 60
	v_readlane_b32 s71, v254, 61
	v_writelane_b32 v254, s2, 25
	v_writelane_b32 v255, s30, 50
	s_lshl_b32 s0, s1, 2
	v_writelane_b32 v254, s3, 26
	v_cmp_gt_u32_e64 s[2:3], v161, v72
	v_writelane_b32 v255, s31, 51
	s_cmp_gt_u32 s38, 1
	v_writelane_b32 v254, s2, 7
	v_cmp_gt_u32_e32 vcc, v162, v70
	s_cselect_b64 s[94:95], -1, 0
	v_writelane_b32 v254, s3, 8
	v_cmp_gt_u32_e64 s[2:3], v161, v73
	s_mov_b32 s1, s53
	v_lshl_add_u64 v[130:131], v[66:67], 0, s[0:1]
	v_writelane_b32 v255, s2, 19
	v_cndmask_b32_e64 v68, 0, 1, s[30:31]
	v_lshlrev_b32_e32 v69, 6, v68
	v_writelane_b32 v255, s3, 20
	v_cmp_gt_u32_e64 s[2:3], v161, v74
	v_lshl_add_u32 v115, v68, 11, v177
	v_or_b32_e32 v68, s40, v69
	v_writelane_b32 v255, s2, 21
	v_mul_u32_u24_e32 v71, 0x110, v70
	v_mov_b32_e32 v134, 0
	v_writelane_b32 v255, s3, 22
	s_or_b64 s[2:3], s[4:5], vcc
	v_writelane_b32 v255, s2, 17
	v_cmp_gt_u32_e32 vcc, v162, v72
	v_cmp_gt_u32_e64 s[0:1], v1, v70
	v_writelane_b32 v255, s3, 18
	s_or_b64 s[2:3], s[4:5], vcc
	v_writelane_b32 v255, s2, 23
	v_cmp_gt_u32_e32 vcc, v162, v73
	v_cmp_gt_u32_e64 s[18:19], v1, v72
	v_writelane_b32 v255, s3, 24
	s_or_b64 s[2:3], s[4:5], vcc
	v_writelane_b32 v255, s2, 52
	v_cmp_gt_u32_e32 vcc, v162, v74
	v_cmp_gt_u32_e64 s[20:21], v1, v73
	v_writelane_b32 v255, s3, 53
	s_or_b64 s[2:3], s[4:5], vcc
	v_cmp_gt_u32_e32 vcc, v164, v70
	v_writelane_b32 v255, s2, 54
	s_or_b64 s[80:81], s[16:17], vcc
	v_cmp_gt_u32_e32 vcc, v164, v72
	v_writelane_b32 v255, s3, 55
	s_or_b64 s[2:3], s[16:17], vcc
	v_cmp_gt_u32_e32 vcc, v164, v73
	s_or_b64 s[68:69], s[16:17], vcc
	v_cmp_gt_u32_e32 vcc, v164, v74
	s_or_b64 s[62:63], s[16:17], vcc
	s_cmp_gt_u32 s38, 5
	v_cmp_gt_u32_e32 vcc, v166, v70
	s_cselect_b64 s[56:57], -1, 0
	s_or_b64 s[16:17], s[36:37], vcc
	v_cmp_gt_u32_e32 vcc, v166, v72
	s_or_b64 s[4:5], s[36:37], vcc
	v_cmp_gt_u32_e32 vcc, v166, v73
	s_or_b64 s[60:61], s[36:37], vcc
	v_cmp_gt_u32_e32 vcc, v166, v74
	s_or_b64 s[58:59], s[36:37], vcc
	s_and_b32 s36, s38, 6
	s_cmp_eq_u32 s36, 6
	s_cselect_b64 s[84:85], -1, 0
	s_add_i32 s36, s40, s33
	v_add_u32_e32 v66, s36, v105
	v_ashrrev_i32_e32 v67, 31, v66
	v_lshlrev_b64 v[136:137], 6, v[66:67]
	s_add_i32 s38, s39, s41
	v_or_b32_e32 v67, v104, v136
	s_add_i32 s38, s38, s43
	v_lshl_or_b32 v136, s42, 5, v67
	v_mad_i64_i32 v[66:67], s[42:43], v66, s44, 0
	v_or_b32_e32 v66, v108, v66
	v_lshl_add_u64 v[138:139], v[66:67], 0, s[52:53]
	v_add_u32_e32 v66, s33, v68
	v_add_u32_e32 v66, v66, v176
	v_ashrrev_i32_e32 v67, 31, v66
	s_ashr_i32 s39, s38, 31
	v_lshlrev_b64 v[68:69], 12, v[66:67]
	s_movk_i32 s33, 0x2e00
	s_lshl_b64 s[38:39], s[38:39], 14
	v_lshl_add_u64 v[68:69], v[110:111], 0, v[68:69]
	v_mad_i64_i32 v[66:67], s[42:43], v66, s33, v[110:111]
	v_cmp_gt_u32_e64 s[22:23], v1, v74
	v_cmp_gt_u32_e64 s[34:35], v163, v70
	v_cmp_gt_u32_e64 s[30:31], v163, v72
	v_mov_b32_e32 v133, s39
	v_or_b32_e32 v132, s38, v106
	v_cmp_gt_u32_e64 s[92:93], v163, v73
	v_cmp_gt_u32_e64 s[96:97], v163, v74
	v_lshl_add_u64 v[142:143], v[68:69], 0, s[52:53]
	v_lshl_add_u64 v[144:145], v[66:67], 0, s[52:53]
	v_readlane_b32 s98, v255, 13
	v_readlane_b32 s99, v255, 14
	s_mov_b64 s[100:101], 0x8c01800
	s_nop 0
	v_lshl_add_u64 v[234:235], s[98:99], 0, v[144:145]
	v_lshl_add_u64 v[236:237], v[234:235], 0, s[100:101]
	global_load_dwordx4 v[226:229], v[236:237], off
	s_mov_b64 s[100:101], 0x8c18800
	v_lshl_add_u64 v[236:237], v[234:235], 0, s[100:101]
	global_load_dwordx4 v[230:233], v[236:237], off
	global_load_dword v240, v[130:131], off
	global_load_dword v241, v[130:131], off offset:64
	global_load_dword v242, v[130:131], off offset:128
	global_load_dword v243, v[130:131], off offset:192
	s_mov_b32 s33, 0
	v_add_u32_e32 v117, v159, v71
	v_mov_b32_e32 v135, v134
	v_mov_b32_e32 v140, v134
	v_mov_b32_e32 v141, v134
	v_cmp_gt_u32_e64 s[78:79], v165, v70
	v_cmp_gt_u32_e64 s[24:25], v165, v72
	v_cmp_gt_u32_e64 s[26:27], v165, v73
	v_cmp_gt_u32_e64 s[28:29], v165, v74
	s_mov_b64 s[64:65], 0
	s_waitcnt vmcnt(0)
	ds_write_b128 v158, v[62:65] offset:26112
	ds_write_b128 v180, v[226:229]
	ds_write_b128 v180, v[230:233] offset:1024
	s_branch .LBB0_1337

.LBB0_1346:
	v_readlane_b32 s36, v254, 63
	v_readlane_b32 s50, v255, 13
	v_readlane_b32 s51, v255, 14
	v_readlane_b32 s37, v255, 0
	v_readlane_b32 s38, v255, 1
	v_lshl_add_u64 v[66:67], s[70:71], 2, v[130:131]
	v_mov_b32_e32 v84, v240
	v_mov_b32_e32 v85, v241
	v_mov_b32_e32 v82, v242
	v_mov_b32_e32 v83, v243
	global_load_dword v238, v99, s[54:55]
	global_load_dword v240, v[66:67], off offset:4
	global_load_dword v241, v[66:67], off offset:68
	global_load_dword v242, v[66:67], off offset:132
	global_load_dword v243, v[66:67], off offset:196
	v_lshl_add_u64 v[70:71], s[50:51], 0, v[144:145]
	v_lshl_add_u64 v[70:71], v[70:71], 0, s[76:77]
	v_add_co_u32_e32 v66, vcc, 0x8c01000, v70
	v_readlane_b32 s39, v255, 2
	s_nop 0
	v_addc_co_u32_e32 v67, vcc, 0, v71, vcc
	v_add_co_u32_e32 v70, vcc, 0x8c18000, v70
	global_load_dwordx4 v[226:229], v[66:67], off offset:2048
	s_nop 0
	v_addc_co_u32_e32 v71, vcc, 0, v71, vcc
	global_load_dwordx4 v[230:233], v[70:71], off offset:2048
	s_and_b64 vcc, exec, s[6:7]
	v_readlane_b32 s40, v255, 3
	v_readlane_b32 s41, v255, 4
	v_readlane_b32 s42, v255, 5
	v_readlane_b32 s43, v255, 6
	v_readlane_b32 s44, v255, 7
	v_readlane_b32 s45, v255, 8
	v_readlane_b32 s46, v255, 9
	v_readlane_b32 s47, v255, 10
	v_readlane_b32 s48, v255, 11
	v_readlane_b32 s49, v255, 12
	v_add_u32_e32 v66, s33, v115
	v_add_u32_e32 v67, 0x1dc00, v66
	s_waitcnt lgkmcnt(0)
	s_barrier
	ds_read_b32 v152, v67
	v_add_u32_e32 v67, 0x1dc20, v66
	ds_read_b32 v153, v67
	v_add_u32_e32 v67, 0x1dc40, v66
	v_add_u32_e32 v66, 0x1dc60, v66
	ds_read_b32 v121, v67
	ds_read_b32 v119, v66
	v_add_u32_e32 v66, s33, v175
	v_add_u32_e32 v67, 0x1dc00, v66
	ds_read_b32 v67, v67
	s_waitcnt lgkmcnt(0)
	v_sub_f32_e32 v68, v152, v67
	v_mul_f32_e32 v68, 0x3fb8aa3b, v68
	v_exp_f32_e32 v68, v68
	s_nop 0
	v_mul_f32_e32 v68, v30, v68
	v_cvt_pk_bf16_f32 v68, v68, s0
	v_cndmask_b32_e64 v68, v68, 0, s[0:1]
	ds_write_b16 v181, v68
	v_sub_f32_e32 v68, v153, v67
	v_mul_f32_e32 v68, 0x3fb8aa3b, v68
	v_exp_f32_e32 v68, v68
	s_nop 0
	v_mul_f32_e32 v68, v31, v68
	v_cvt_pk_bf16_f32 v68, v68, s0
	v_cndmask_b32_e64 v68, v68, 0, s[18:19]
	ds_write_b16 v181, v68 offset:272
	v_sub_f32_e32 v68, v121, v67
	v_sub_f32_e32 v67, v119, v67
	v_mul_f32_e32 v67, 0x3fb8aa3b, v67
	v_exp_f32_e32 v67, v67
	v_mul_f32_e32 v68, 0x3fb8aa3b, v68
	v_exp_f32_e32 v68, v68
	v_mul_f32_e32 v67, v33, v67
	v_cvt_pk_bf16_f32 v67, v67, s0
	v_cndmask_b32_e64 v67, v67, 0, s[22:23]
	ds_write_b16 v181, v67 offset:816
	v_add_u32_e32 v67, 0x1de00, v66
	ds_read_b32 v67, v67
	v_mul_f32_e32 v68, v32, v68
	v_cvt_pk_bf16_f32 v68, v68, s0
	v_cndmask_b32_e64 v68, v68, 0, s[20:21]
	ds_write_b16 v181, v68 offset:544
	s_waitcnt lgkmcnt(1)
	v_sub_f32_e32 v68, v152, v67
	v_mul_f32_e32 v68, 0x3fb8aa3b, v68
	v_exp_f32_e32 v68, v68
	s_nop 0
	v_mul_f32_e32 v68, v2, v68
	v_cvt_pk_bf16_f32 v68, v68, s0
	v_cndmask_b32_e64 v68, v68, 0, s[82:83]
	ds_write_b16 v181, v68 offset:32
	v_sub_f32_e32 v68, v153, v67
	v_mul_f32_e32 v68, 0x3fb8aa3b, v68
	v_exp_f32_e32 v68, v68
	s_nop 0
	v_mul_f32_e32 v68, v3, v68
	v_cvt_pk_bf16_f32 v68, v68, s0
	v_cndmask_b32_e64 v68, v68, 0, s[86:87]
	ds_write_b16 v181, v68 offset:304
	v_sub_f32_e32 v68, v121, v67
	v_sub_f32_e32 v67, v119, v67
	v_mul_f32_e32 v68, 0x3fb8aa3b, v68
	v_mul_f32_e32 v67, 0x3fb8aa3b, v67
	v_exp_f32_e32 v68, v68
	v_exp_f32_e32 v67, v67
	v_mul_f32_e32 v68, v4, v68
	v_mul_f32_e32 v67, v5, v67
	v_cvt_pk_bf16_f32 v68, v68, s0
	v_cvt_pk_bf16_f32 v67, v67, s0
	v_cndmask_b32_e64 v68, v68, 0, s[88:89]
	v_cndmask_b32_e64 v67, v67, 0, s[90:91]
	ds_write_b16 v181, v68 offset:576
	ds_write_b16 v181, v67 offset:848
	s_cbranch_vccnz .LBB0_1350
	v_add_u32_e32 v67, 0x1e000, v66
	ds_read_b32 v67, v67
	v_readlane_b32 s36, v254, 25
	v_readlane_b32 s37, v254, 26
	s_waitcnt lgkmcnt(0)
	v_sub_f32_e32 v68, v152, v67
	v_mul_f32_e32 v68, 0x3fb8aa3b, v68
	v_exp_f32_e32 v68, v68
	s_nop 0
	v_mul_f32_e32 v68, v6, v68
	v_cvt_pk_bf16_f32 v68, v68, s0
	v_cndmask_b32_e64 v68, v68, 0, s[36:37]
	ds_write_b16 v181, v68 offset:64
	v_sub_f32_e32 v68, v153, v67
	v_mul_f32_e32 v68, 0x3fb8aa3b, v68
	v_exp_f32_e32 v68, v68
	v_readlane_b32 s36, v254, 7
	v_readlane_b32 s37, v254, 8
	v_mul_f32_e32 v68, v7, v68
	v_cvt_pk_bf16_f32 v68, v68, s0
	v_cndmask_b32_e64 v68, v68, 0, s[36:37]
	ds_write_b16 v181, v68 offset:336
	v_sub_f32_e32 v68, v121, v67
	v_mul_f32_e32 v68, 0x3fb8aa3b, v68
	v_exp_f32_e32 v68, v68
	v_sub_f32_e32 v67, v119, v67
	v_mul_f32_e32 v67, 0x3fb8aa3b, v67
	v_exp_f32_e32 v67, v67
	v_mul_f32_e32 v68, v8, v68
	v_readlane_b32 s36, v255, 19
	v_cvt_pk_bf16_f32 v68, v68, s0
	v_readlane_b32 s37, v255, 20
	v_mul_f32_e32 v67, v9, v67
	v_cvt_pk_bf16_f32 v67, v67, s0
	v_cndmask_b32_e64 v68, v68, 0, s[36:37]
	v_readlane_b32 s36, v255, 21
	v_readlane_b32 s37, v255, 22
	ds_write_b16 v181, v68 offset:608
	s_nop 0
	v_cndmask_b32_e64 v67, v67, 0, s[36:37]
	ds_write_b16 v181, v67 offset:880
	s_andn2_b64 vcc, exec, s[94:95]
	s_cbranch_vccz .LBB0_1351

.LBB0_1358:
	s_nop 0
	v_div_scale_f32 v86, s[70:71], v85, v85, 1.0
	v_rcp_f32_e32 v87, v86
	v_add_u32_e32 v148, s73, v125
	ds_read_b128 v[184:187], v148 offset:65280
	v_mul_f32_e32 v152, 0x3fb8aa3b, v152
	v_fma_f32 v88, -v86, v87, 1.0
	v_fmac_f32_e32 v87, v88, v87
	v_div_scale_f32 v88, vcc, 1.0, v85, 1.0
	v_mul_f32_e32 v89, v88, v87
	v_fma_f32 v90, -v86, v89, v88
	v_fmac_f32_e32 v89, v90, v87
	v_fma_f32 v86, -v86, v89, v88
	v_div_fmas_f32 v86, v86, v87, v89
	v_div_fixup_f32 v151, v86, v85, 1.0
	v_div_scale_f32 v85, s[70:71], v84, v84, 1.0
	v_rcp_f32_e32 v86, v85
	ds_read_b128 v[90:93], v148 offset:56576
	ds_read_b128 v[94:97], v148 offset:60928
	v_mul_f32_e32 v153, 0x3fb8aa3b, v153
	v_fma_f32 v87, -v85, v86, 1.0
	v_fmac_f32_e32 v86, v87, v86
	v_div_scale_f32 v87, vcc, 1.0, v84, 1.0
	v_mul_f32_e32 v88, v87, v86
	v_fma_f32 v89, -v85, v88, v87
	v_fmac_f32_e32 v88, v89, v86
	v_fma_f32 v85, -v85, v88, v87
	v_div_fmas_f32 v85, v85, v86, v88
	v_div_fixup_f32 v150, v85, v84, 1.0
	s_nop 0
	v_div_scale_f32 v84, s[70:71], v83, v83, 1.0
	v_rcp_f32_e32 v85, v84
	v_exp_f32_e32 v152, v152
	v_exp_f32_e32 v153, v153
	v_readlane_b32 s36, v254, 63
	v_fma_f32 v86, -v84, v85, 1.0
	v_fmac_f32_e32 v85, v86, v85
	v_div_scale_f32 v86, vcc, 1.0, v83, 1.0
	v_mul_f32_e32 v87, v86, v85
	v_fma_f32 v88, -v84, v87, v86
	v_fmac_f32_e32 v87, v88, v85
	v_fma_f32 v84, -v84, v87, v86
	v_div_fmas_f32 v84, v84, v85, v87
	v_div_fixup_f32 v147, v84, v83, 1.0
	v_div_scale_f32 v83, s[70:71], v82, v82, 1.0
	v_rcp_f32_e32 v84, v83
	v_readlane_b32 s50, v255, 13
	v_readlane_b32 s51, v255, 14
	v_readlane_b32 s37, v255, 0
	v_fma_f32 v85, -v83, v84, 1.0
	v_fmac_f32_e32 v84, v85, v84
	v_div_scale_f32 v85, vcc, 1.0, v82, 1.0
	v_mul_f32_e32 v86, v85, v84
	v_fma_f32 v87, -v83, v86, v85
	v_fmac_f32_e32 v86, v87, v84
	v_fma_f32 v83, -v83, v86, v85
	v_div_fmas_f32 v83, v83, v84, v86
	v_div_fixup_f32 v146, v83, v82, 1.0
	ds_read_b128 v[82:85], v113
	ds_read_b128 v[86:89], v148 offset:52224
	s_waitcnt lgkmcnt(0)
	v_mfma_f32_16x16x32_bf16 v[86:89], v[82:85], v[86:89], 0
	v_readlane_b32 s38, v255, 1
	v_readlane_b32 s39, v255, 2
	v_readlane_b32 s40, v255, 3
	v_mfma_f32_16x16x32_bf16 v[90:93], v[82:85], v[90:93], 0
	v_readlane_b32 s41, v255, 4
	v_readlane_b32 s42, v255, 5
	v_readlane_b32 s43, v255, 6
	v_mfma_f32_16x16x32_bf16 v[94:97], v[82:85], v[94:97], 0
	v_readlane_b32 s44, v255, 7
	v_readlane_b32 s45, v255, 8
	v_readlane_b32 s46, v255, 9
	v_mfma_f32_16x16x32_bf16 v[82:85], v[82:85], v[184:187], 0
	ds_read_b128 v[184:187], v113 offset:64
	ds_read_b128 v[188:191], v148 offset:52288
	v_readlane_b32 s47, v255, 10
	v_readlane_b32 s48, v255, 11
	s_waitcnt lgkmcnt(0)
	v_mfma_f32_16x16x32_bf16 v[86:89], v[184:187], v[188:191], v[86:89]
	ds_read_b128 v[188:191], v148 offset:56640
	v_readlane_b32 s49, v255, 12
	s_waitcnt lgkmcnt(0)
	v_mfma_f32_16x16x32_bf16 v[90:93], v[184:187], v[188:191], v[90:93]
	ds_read_b128 v[188:191], v148 offset:60992
	s_waitcnt lgkmcnt(0)
	v_mfma_f32_16x16x32_bf16 v[94:97], v[184:187], v[188:191], v[94:97]
	ds_read_b128 v[188:191], v148 offset:65344
	s_waitcnt lgkmcnt(0)
	v_mfma_f32_16x16x32_bf16 v[82:85], v[184:187], v[188:191], v[82:85]
	ds_read_b128 v[184:187], v113 offset:128
	ds_read_b128 v[188:191], v148 offset:52352
	s_waitcnt lgkmcnt(0)
	v_mfma_f32_16x16x32_bf16 v[86:89], v[184:187], v[188:191], v[86:89]
	ds_read_b128 v[188:191], v148 offset:56704
	s_waitcnt lgkmcnt(0)
	v_mfma_f32_16x16x32_bf16 v[90:93], v[184:187], v[188:191], v[90:93]
	ds_read_b128 v[188:191], v148 offset:61056
	s_waitcnt lgkmcnt(0)
	v_mfma_f32_16x16x32_bf16 v[188:191], v[184:187], v[188:191], v[94:97]
	s_nop 2
	ds_read_b128 v[94:97], v148 offset:65408
	s_waitcnt lgkmcnt(0)
	v_mfma_f32_16x16x32_bf16 v[82:85], v[184:187], v[94:97], v[82:85]
	ds_read_b128 v[184:187], v113 offset:192
	ds_read_b128 v[94:97], v148 offset:52416
	s_waitcnt lgkmcnt(0)
	v_mfma_f32_16x16x32_bf16 v[94:97], v[184:187], v[94:97], v[86:89]
	s_nop 2
	ds_read_b128 v[86:89], v148 offset:56768
	s_waitcnt lgkmcnt(0)
	v_mfma_f32_16x16x32_bf16 v[90:93], v[184:187], v[86:89], v[90:93]
	ds_read_b128 v[86:89], v148 offset:61120
	s_nop 0
	v_pk_fma_f32 v[78:79], v[152:153], v[94:95], v[78:79]
	s_nop 4
	v_pk_fma_f32 v[90:91], v[152:153], v[90:91], v[74:75]
	s_waitcnt lgkmcnt(0)
	v_mfma_f32_16x16x32_bf16 v[86:89], v[184:187], v[86:89], v[188:191]
	s_nop 2
	ds_read_b128 v[188:191], v148 offset:65472
	s_waitcnt lgkmcnt(0)
	v_mfma_f32_16x16x32_bf16 v[82:85], v[184:187], v[188:191], v[82:85]
	ds_read_u16 v183, v117 offset:17408
	ds_read_u16 v187, v117 offset:17440
	ds_read_u16 v184, v178
	ds_read_u16 v185, v178 offset:32
	ds_read_u16 v190, v117 offset:17472
	ds_read_u16 v191, v178 offset:64
	ds_read_u16 v192, v117 offset:17504
	ds_read_u16 v186, v178 offset:96
	ds_read_u16 v188, v117 offset:17680
	ds_read_u16 v189, v178 offset:128
	ds_read_u16 v193, v117 offset:17712
	ds_read_u16 v194, v178 offset:160
	ds_read_u16 v195, v117 offset:17744
	ds_read_u16 v196, v178 offset:192
	ds_read_u16 v197, v117 offset:17776
	ds_read_u16 v198, v178 offset:224
	s_waitcnt lgkmcnt(13)
	v_lshlrev_b32_e32 v200, 16, v184
	s_waitcnt lgkmcnt(12)
	v_lshlrev_b32_e32 v201, 16, v185
	v_mul_f32_e32 v184, 0xbfb8aa3b, v200
	v_mul_f32_e32 v185, 0xbfb8aa3b, v201
	s_waitcnt lgkmcnt(8)
	v_lshlrev_b32_e32 v199, 16, v186
	v_exp_f32_e32 v184, v184
	v_exp_f32_e32 v186, v185
	s_waitcnt lgkmcnt(4)
	v_lshlrev_b32_e32 v194, 16, v194
	v_mul_f32_e32 v74, 0xbfb8aa3b, v194
	v_pk_fma_f32 v[70:71], v[152:153], v[86:87], v[70:71]
	s_waitcnt lgkmcnt(0)
	v_lshlrev_b32_e32 v198, 16, v198
	v_pk_fma_f32 v[66:67], v[152:153], v[82:83], v[66:67]
	v_mul_f32_e32 v82, 0xbfb8aa3b, v198
	s_waitcnt vmcnt(6)
	v_mov_b32_e32 v148, v238
	v_pk_mul_f32 v[154:155], v[150:151], v[148:149] op_sel_hi:[1,0]
	v_lshlrev_b32_e32 v151, 16, v189
	v_mul_f32_e32 v94, 0xbfb8aa3b, v151
	v_exp_f32_e32 v185, v94
	v_lshlrev_b32_e32 v189, 16, v188
	v_lshlrev_b32_e32 v188, 16, v183
	v_mul_f32_e32 v150, 0xbfb8aa3b, v199
	v_pk_add_f32 v[94:95], v[184:185], 1.0 op_sel_hi:[1,0]
	v_exp_f32_e32 v150, v150
	v_div_scale_f32 v183, s[70:71], v95, v95, v151
	v_rcp_f32_e32 v184, v183
	s_nop 0
	v_fma_f32 v185, -v183, v184, 1.0
	v_fmac_f32_e32 v184, v185, v184
	v_div_scale_f32 v185, vcc, v151, v95, v151
	v_mul_f32_e32 v202, v185, v184
	v_fma_f32 v203, -v183, v202, v185
	v_fmac_f32_e32 v202, v203, v184
	v_fma_f32 v183, -v183, v202, v185
	v_div_fmas_f32 v183, v183, v184, v202
	v_div_fixup_f32 v95, v183, v95, v151
	v_div_scale_f32 v151, s[70:71], v94, v94, v200
	v_rcp_f32_e32 v183, v151
	s_nop 0
	v_fma_f32 v184, -v151, v183, 1.0
	v_fmac_f32_e32 v183, v184, v183
	v_div_scale_f32 v184, vcc, v200, v94, v200
	v_mul_f32_e32 v185, v184, v183
	v_fma_f32 v202, -v151, v185, v184
	v_fmac_f32_e32 v185, v202, v183
	v_fma_f32 v151, -v151, v185, v184
	v_lshlrev_b32_e32 v184, 16, v187
	v_exp_f32_e32 v187, v74
	v_div_fmas_f32 v151, v151, v183, v185
	v_div_fixup_f32 v94, v151, v94, v200
	v_lshlrev_b32_e32 v185, 16, v193
	v_pk_add_f32 v[74:75], v[186:187], 1.0 op_sel_hi:[1,0]
	s_nop 0
	v_div_scale_f32 v151, s[70:71], v75, v75, v194
	v_rcp_f32_e32 v183, v151
	s_nop 0
	v_fma_f32 v186, -v151, v183, 1.0
	v_fmac_f32_e32 v183, v186, v183
	v_div_scale_f32 v186, vcc, v194, v75, v194
	v_mul_f32_e32 v187, v186, v183
	v_fma_f32 v193, -v151, v187, v186
	v_fmac_f32_e32 v187, v193, v183
	v_fma_f32 v151, -v151, v187, v186
	v_div_fmas_f32 v151, v151, v183, v187
	v_div_fixup_f32 v187, v151, v75, v194
	v_div_scale_f32 v75, s[70:71], v74, v74, v201
	v_rcp_f32_e32 v151, v75
	s_nop 0
	v_fma_f32 v183, -v75, v151, 1.0
	v_fmac_f32_e32 v151, v183, v151
	v_div_scale_f32 v183, vcc, v201, v74, v201
	v_mul_f32_e32 v186, v183, v151
	v_fma_f32 v193, -v75, v186, v183
	v_fmac_f32_e32 v186, v193, v151
	v_fma_f32 v75, -v75, v186, v183
	v_div_fmas_f32 v75, v75, v151, v186
	v_lshlrev_b32_e32 v151, 16, v196
	v_lshlrev_b32_e32 v183, 16, v191
	v_div_fixup_f32 v186, v75, v74, v201
	v_pk_fma_f32 v[74:75], v[154:155], v[188:189], v[78:79]
	v_pk_fma_f32 v[78:79], v[154:155], v[184:185], v[90:91]
	v_mul_f32_e32 v90, 0xbfb8aa3b, v183
	v_mul_f32_e32 v86, 0xbfb8aa3b, v151
	v_exp_f32_e32 v90, v90
	v_exp_f32_e32 v91, v86
	v_pk_mul_f32 v[78:79], v[78:79], v[186:187]
	v_pk_mul_f32 v[74:75], v[74:75], v[94:95]
	v_lshlrev_b32_e32 v95, 16, v195
	v_pk_add_f32 v[86:87], v[90:91], 1.0 op_sel_hi:[1,0]
	v_lshlrev_b32_e32 v94, 16, v190
	v_div_scale_f32 v90, s[70:71], v87, v87, v151
	v_rcp_f32_e32 v91, v90
	v_pk_fma_f32 v[70:71], v[154:155], v[94:95], v[70:71]
	v_fma_f32 v184, -v90, v91, 1.0
	v_fmac_f32_e32 v91, v184, v91
	v_div_scale_f32 v184, vcc, v151, v87, v151
	v_mul_f32_e32 v185, v184, v91
	v_fma_f32 v186, -v90, v185, v184
	v_fmac_f32_e32 v185, v186, v91
	v_fma_f32 v90, -v90, v185, v184
	v_div_fmas_f32 v90, v90, v91, v185
	v_div_fixup_f32 v87, v90, v87, v151
	v_div_scale_f32 v90, s[70:71], v86, v86, v183
	v_rcp_f32_e32 v91, v90
	s_nop 0
	v_fma_f32 v151, -v90, v91, 1.0
	v_fmac_f32_e32 v91, v151, v91
	v_div_scale_f32 v151, vcc, v183, v86, v183
	v_mul_f32_e32 v184, v151, v91
	v_fma_f32 v185, -v90, v184, v151
	v_fmac_f32_e32 v184, v185, v91
	v_fma_f32 v90, -v90, v184, v151
	v_exp_f32_e32 v151, v82
	v_div_fmas_f32 v90, v90, v91, v184
	v_div_fixup_f32 v86, v90, v86, v183
	v_pk_mul_f32 v[70:71], v[70:71], v[86:87]
	v_lshlrev_b32_e32 v87, 16, v197
	v_lshlrev_b32_e32 v86, 16, v192
	v_pk_add_f32 v[82:83], v[150:151], 1.0 op_sel_hi:[1,0]
	v_pk_fma_f32 v[66:67], v[154:155], v[86:87], v[66:67]
	v_div_scale_f32 v86, s[70:71], v83, v83, v198
	v_rcp_f32_e32 v87, v86
	s_nop 0
	v_fma_f32 v90, -v86, v87, 1.0
	v_fmac_f32_e32 v87, v90, v87
	v_div_scale_f32 v90, vcc, v198, v83, v198
	v_mul_f32_e32 v91, v90, v87
	v_fma_f32 v94, -v86, v91, v90
	v_fmac_f32_e32 v91, v94, v87
	v_fma_f32 v86, -v86, v91, v90
	v_div_fmas_f32 v86, v86, v87, v91
	v_div_fixup_f32 v83, v86, v83, v198
	v_div_scale_f32 v86, s[70:71], v82, v82, v199
	v_rcp_f32_e32 v87, v86
	s_nop 0
	v_fma_f32 v90, -v86, v87, 1.0
	v_fmac_f32_e32 v87, v90, v87
	v_div_scale_f32 v90, vcc, v199, v82, v199
	v_mul_f32_e32 v91, v90, v87
	v_fma_f32 v94, -v86, v91, v90
	v_fmac_f32_e32 v91, v94, v87
	v_fma_f32 v86, -v86, v91, v90
	v_div_fmas_f32 v86, v86, v87, v91
	v_div_fixup_f32 v82, v86, v82, v199
	v_pk_mul_f32 v[66:67], v[66:67], v[82:83]
	v_mul_f32_e32 v82, 0x3fb8aa3b, v121
	ds_read_u16 v87, v117 offset:17952
	ds_read_u16 v94, v178 offset:256
	ds_read_u16 v121, v117 offset:17984
	ds_read_u16 v95, v178 offset:288
	ds_read_u16 v152, v117 offset:18016
	ds_read_u16 v153, v178 offset:320
	ds_read_u16 v154, v117 offset:18048
	ds_read_u16 v86, v178 offset:352
	v_mul_f32_e32 v83, 0x3fb8aa3b, v119
	ds_read_u16 v119, v117 offset:18224
	ds_read_u16 v150, v178 offset:384
	ds_read_u16 v155, v117 offset:18256
	ds_read_u16 v151, v178 offset:416
	ds_read_u16 v183, v117 offset:18288
	ds_read_u16 v184, v178 offset:448
	ds_read_u16 v185, v117 offset:18320
	ds_read_u16 v186, v178 offset:480
	v_pk_mul_f32 v[90:91], v[146:147], v[148:149] op_sel_hi:[1,0]
	s_waitcnt lgkmcnt(6)
	v_lshlrev_b32_e32 v147, 16, v150
	v_lshlrev_b32_e32 v187, 16, v94
	v_lshlrev_b32_e32 v189, 16, v95
	v_mul_f32_e32 v94, 0xbfb8aa3b, v187
	v_mul_f32_e32 v95, 0xbfb8aa3b, v189
	v_lshlrev_b32_e32 v150, 16, v87
	v_mul_f32_e32 v87, 0xbfb8aa3b, v147
	v_exp_f32_e32 v94, v94
	v_exp_f32_e32 v146, v95
	v_exp_f32_e32 v95, v87
	v_exp_f32_e32 v82, v82
	v_exp_f32_e32 v83, v83
	s_waitcnt lgkmcnt(4)
	v_lshlrev_b32_e32 v188, 16, v151
	v_pk_add_f32 v[94:95], v[94:95], 1.0 op_sel_hi:[1,0]
	v_lshlrev_b32_e32 v151, 16, v119
	v_div_scale_f32 v87, s[70:71], v95, v95, v147
	v_pk_fma_f32 v[80:81], v[82:83], v[96:97], v[80:81]
	v_rcp_f32_e32 v96, v87
	v_pk_fma_f32 v[92:93], v[82:83], v[92:93], v[76:77]
	v_mul_f32_e32 v76, 0xbfb8aa3b, v188
	v_pk_fma_f32 v[72:73], v[82:83], v[88:89], v[72:73]
	v_fma_f32 v97, -v87, v96, 1.0
	v_fmac_f32_e32 v96, v97, v96
	v_div_scale_f32 v97, vcc, v147, v95, v147
	v_mul_f32_e32 v119, v97, v96
	v_fma_f32 v190, -v87, v119, v97
	v_fmac_f32_e32 v119, v190, v96
	v_fma_f32 v87, -v87, v119, v97
	v_div_fmas_f32 v87, v87, v96, v119
	v_div_fixup_f32 v95, v87, v95, v147
	v_div_scale_f32 v87, s[70:71], v94, v94, v187
	v_rcp_f32_e32 v96, v87
	s_waitcnt lgkmcnt(0)
	v_lshlrev_b32_e32 v148, 16, v186
	v_lshlrev_b32_e32 v186, 16, v86
	v_mul_f32_e32 v86, 0xbfb8aa3b, v186
	v_fma_f32 v97, -v87, v96, 1.0
	v_fmac_f32_e32 v96, v97, v96
	v_div_scale_f32 v97, vcc, v187, v94, v187
	v_mul_f32_e32 v119, v97, v96
	v_fma_f32 v147, -v87, v119, v97
	v_fmac_f32_e32 v119, v147, v96
	v_exp_f32_e32 v147, v76
	v_fma_f32 v87, -v87, v119, v97
	v_div_fmas_f32 v87, v87, v96, v119
	v_div_fixup_f32 v94, v87, v94, v187
	v_pk_add_f32 v[76:77], v[146:147], 1.0 op_sel_hi:[1,0]
	v_lshlrev_b32_e32 v96, 16, v121
	v_div_scale_f32 v87, s[70:71], v77, v77, v188
	v_rcp_f32_e32 v119, v87
	v_lshlrev_b32_e32 v97, 16, v155
	v_pk_fma_f32 v[68:69], v[82:83], v[84:85], v[68:69]
	v_mul_f32_e32 v82, 0xbfb8aa3b, v148
	v_fma_f32 v121, -v87, v119, 1.0
	v_fmac_f32_e32 v119, v121, v119
	v_div_scale_f32 v121, vcc, v188, v77, v188
	v_mul_f32_e32 v146, v121, v119
	v_fma_f32 v147, -v87, v146, v121
	v_fmac_f32_e32 v146, v147, v119
	v_fma_f32 v87, -v87, v146, v121
	v_div_fmas_f32 v87, v87, v119, v146
	v_div_fixup_f32 v147, v87, v77, v188
	v_div_scale_f32 v77, s[70:71], v76, v76, v189
	v_rcp_f32_e32 v87, v77
	v_exp_f32_e32 v86, v86
	s_waitcnt lgkmcnt(0)
	v_fma_f32 v119, -v77, v87, 1.0
	v_fmac_f32_e32 v87, v119, v87
	v_div_scale_f32 v119, vcc, v189, v76, v189
	v_mul_f32_e32 v121, v119, v87
	v_fma_f32 v146, -v77, v121, v119
	v_fmac_f32_e32 v121, v146, v87
	v_fma_f32 v77, -v77, v121, v119
	v_div_fmas_f32 v77, v77, v87, v121
	v_div_fixup_f32 v146, v77, v76, v189
	v_pk_fma_f32 v[76:77], v[90:91], v[150:151], v[80:81]
	v_pk_fma_f32 v[80:81], v[90:91], v[96:97], v[92:93]
	v_lshlrev_b32_e32 v87, 16, v184
	v_lshlrev_b32_e32 v96, 16, v153
	v_mul_f32_e32 v92, 0xbfb8aa3b, v96
	v_mul_f32_e32 v88, 0xbfb8aa3b, v87
	v_exp_f32_e32 v92, v92
	v_exp_f32_e32 v93, v88
	v_pk_mul_f32 v[76:77], v[76:77], v[94:95]
	v_lshlrev_b32_e32 v95, 16, v183
	v_lshlrev_b32_e32 v94, 16, v152
	v_pk_add_f32 v[88:89], v[92:93], 1.0 op_sel_hi:[1,0]
	v_pk_fma_f32 v[72:73], v[90:91], v[94:95], v[72:73]
	v_div_scale_f32 v92, s[70:71], v89, v89, v87
	v_rcp_f32_e32 v93, v92
	v_pk_mul_f32 v[80:81], v[80:81], v[146:147]
	v_fma_f32 v97, -v92, v93, 1.0
	v_fmac_f32_e32 v93, v97, v93
	v_div_scale_f32 v97, vcc, v87, v89, v87
	v_mul_f32_e32 v119, v97, v93
	v_fma_f32 v121, -v92, v119, v97
	v_fmac_f32_e32 v119, v121, v93
	v_fma_f32 v92, -v92, v119, v97
	v_div_fmas_f32 v92, v92, v93, v119
	v_div_fixup_f32 v89, v92, v89, v87
	v_div_scale_f32 v87, s[70:71], v88, v88, v96
	v_rcp_f32_e32 v92, v87
	s_nop 0
	v_fma_f32 v93, -v87, v92, 1.0
	v_fmac_f32_e32 v92, v93, v92
	v_div_scale_f32 v93, vcc, v96, v88, v96
	v_mul_f32_e32 v97, v93, v92
	v_fma_f32 v119, -v87, v97, v93
	v_fmac_f32_e32 v97, v119, v92
	v_fma_f32 v87, -v87, v97, v93
	v_div_fmas_f32 v87, v87, v92, v97
	v_div_fixup_f32 v88, v87, v88, v96
	v_exp_f32_e32 v87, v82
	v_pk_mul_f32 v[72:73], v[72:73], v[88:89]
	v_lshlrev_b32_e32 v89, 16, v185
	v_lshlrev_b32_e32 v88, 16, v154
	v_pk_add_f32 v[82:83], v[86:87], 1.0 op_sel_hi:[1,0]
	v_pk_fma_f32 v[68:69], v[90:91], v[88:89], v[68:69]
	v_div_scale_f32 v84, s[70:71], v83, v83, v148
	v_rcp_f32_e32 v85, v84
	v_lshl_add_u64 v[90:91], s[50:51], 0, v[142:143]
	v_fma_f32 v86, -v84, v85, 1.0
	v_fmac_f32_e32 v85, v86, v85
	v_div_scale_f32 v86, vcc, v148, v83, v148
	v_mul_f32_e32 v87, v86, v85
	v_fma_f32 v88, -v84, v87, v86
	v_fmac_f32_e32 v87, v88, v85
	v_fma_f32 v84, -v84, v87, v86
	v_div_fmas_f32 v84, v84, v85, v87
	v_div_fixup_f32 v83, v84, v83, v148
	v_div_scale_f32 v84, s[70:71], v82, v82, v186
	v_rcp_f32_e32 v85, v84
	s_nop 0
	v_fma_f32 v86, -v84, v85, 1.0
	v_fmac_f32_e32 v85, v86, v85
	v_div_scale_f32 v86, vcc, v186, v82, v186
	v_mul_f32_e32 v87, v86, v85
	v_fma_f32 v88, -v84, v87, v86
	v_fmac_f32_e32 v87, v88, v85
	v_fma_f32 v84, -v84, v87, v86
	v_div_fmas_f32 v84, v84, v85, v87
	v_div_fixup_f32 v82, v84, v82, v186
	v_pk_mul_f32 v[68:69], v[68:69], v[82:83]
	v_cvt_pk_bf16_f32 v82, v74, s0
	ds_write_b16 v178, v82
	v_cvt_pk_bf16_f32 v82, v78, s0
	ds_write_b16 v178, v82 offset:32
	v_cvt_pk_bf16_f32 v82, v70, s0
	ds_write_b16 v178, v82 offset:64
	v_cvt_pk_bf16_f32 v82, v66, s0
	ds_write_b16 v178, v82 offset:96
	v_cvt_pk_bf16_f32 v82, v75, s0
	ds_write_b16 v178, v82 offset:128
	v_cvt_pk_bf16_f32 v82, v79, s0
	ds_write_b16 v178, v82 offset:160
	v_cvt_pk_bf16_f32 v82, v71, s0
	ds_write_b16 v178, v82 offset:192
	v_cvt_pk_bf16_f32 v82, v67, s0
	ds_write_b16 v178, v82 offset:224
	v_cvt_pk_bf16_f32 v82, v76, s0
	ds_write_b16 v178, v82 offset:256
	v_cvt_pk_bf16_f32 v82, v80, s0
	ds_write_b16 v178, v82 offset:288
	v_cvt_pk_bf16_f32 v82, v72, s0
	ds_write_b16 v178, v82 offset:320
	v_cvt_pk_bf16_f32 v82, v68, s0
	ds_write_b16 v178, v82 offset:352
	v_cvt_pk_bf16_f32 v82, v77, s0
	ds_write_b16 v178, v82 offset:384
	v_cvt_pk_bf16_f32 v82, v81, s0
	ds_write_b16 v178, v82 offset:416
	v_cvt_pk_bf16_f32 v82, v73, s0
	ds_write_b16 v178, v82 offset:448
	v_cvt_pk_bf16_f32 v82, v69, s0
	ds_write_b16 v178, v82 offset:480
	s_waitcnt lgkmcnt(0)
	ds_read_b128 v[82:85], v180
	ds_read_b128 v[86:89], v180 offset:1024
	v_add_co_u32_e32 v92, vcc, 0x10000000, v90
	s_nop 1
	v_addc_co_u32_e32 v93, vcc, 0, v91, vcc
	s_waitcnt lgkmcnt(1)
	global_store_dwordx4 v[92:93], v[82:85], off offset:2048
	s_nop 1
	v_add_co_u32_e32 v82, vcc, 0x10008000, v90
	s_nop 1
	v_addc_co_u32_e32 v83, vcc, 0, v91, vcc
	s_andn2_b64 vcc, exec, s[66:67]
	s_waitcnt lgkmcnt(0)
	global_store_dwordx4 v[82:83], v[86:89], off offset:2048
	s_barrier
	s_waitcnt vmcnt(2)
	ds_write_b128 v180, v[226:229]
	ds_write_b128 v180, v[230:233] offset:1024
	s_cbranch_vccnz .LBB0_1336
	v_lshlrev_b32_e32 v82, 16, v38
	v_and_b32_e32 v83, 0xffff0000, v38
	v_lshlrev_b32_e32 v84, 16, v39
	v_and_b32_e32 v85, 0xffff0000, v39
	v_pk_mul_f32 v[82:83], v[122:123], v[82:83] op_sel_hi:[0,1]
	v_pk_mul_f32 v[84:85], v[122:123], v[84:85] op_sel_hi:[0,1]
	v_cvt_pk_bf16_f32 v82, v82, v83
	v_cvt_pk_bf16_f32 v83, v84, v85
	v_lshlrev_b32_e32 v84, 16, v40
	v_and_b32_e32 v85, 0xffff0000, v40
	v_lshlrev_b32_e32 v86, 16, v41
	v_and_b32_e32 v87, 0xffff0000, v41
	v_pk_mul_f32 v[84:85], v[122:123], v[84:85] op_sel_hi:[0,1]
	v_pk_mul_f32 v[86:87], v[122:123], v[86:87] op_sel_hi:[0,1]
	v_cvt_pk_bf16_f32 v84, v84, v85
	v_cvt_pk_bf16_f32 v85, v86, v87
	ds_write_b128 v127, v[82:85] offset:17408
	ds_write_b128 v127, v[42:45] offset:52224
	s_and_saveexec_b64 s[66:67], s[10:11]
	s_cbranch_execz .LBB0_1364
	v_lshlrev_b32_e32 v82, 16, v34
	v_and_b32_e32 v83, 0xffff0000, v34
	v_lshlrev_b32_e32 v84, 16, v35
	v_and_b32_e32 v85, 0xffff0000, v35
	v_pk_mul_f32 v[82:83], v[124:125], v[82:83] op_sel_hi:[0,1]
	v_pk_mul_f32 v[84:85], v[124:125], v[84:85] op_sel_hi:[0,1]
	v_cvt_pk_bf16_f32 v82, v82, v83
	v_cvt_pk_bf16_f32 v83, v84, v85
	v_lshlrev_b32_e32 v84, 16, v36
	v_and_b32_e32 v85, 0xffff0000, v36
	v_lshlrev_b32_e32 v86, 16, v37
	v_and_b32_e32 v87, 0xffff0000, v37
	v_pk_mul_f32 v[84:85], v[124:125], v[84:85] op_sel_hi:[0,1]
	v_pk_mul_f32 v[86:87], v[124:125], v[86:87] op_sel_hi:[0,1]
	v_cvt_pk_bf16_f32 v84, v84, v85
	v_cvt_pk_bf16_f32 v85, v86, v87
	ds_write_b128 v127, v[82:85] offset:26112
	s_or_b64 exec, exec, s[66:67]
	ds_write_b128 v127, v[54:57] offset:60928
	s_and_saveexec_b64 s[66:67], s[12:13]
	s_cbranch_execnz .LBB0_1365
